# moba_select by hand (LDS-staged block sums, packed f32 dots, pairwise rank), carry-outs to vcc
# speedup vs baseline: 1.0021x; 1.0021x over previous
; __device__ __forceinline__ unsigned moba_select(int b, int h, int qb, const f16_t* Q, const float* __restrict__ kms) {
;     int tid_ = threadIdx.x; asm volatile("" : "+v"(tid_));
;     const int tid = tid_, lane = tid & 63, r32 = lane & 31, hi = lane >> 5; const int wid = __builtin_amdgcn_readfirstlane(tid >> 6);
;     const f16_t* Qw = Q + ((long)b * SEQ + qb * QB + wid * QBLK) * QP + h * HD;
;     f16x8 qr[4];
; #pragma unroll
;     for (int d0 = 0; d0 < 4; ++d0) qr[d0] = *reinterpret_cast<const f16x8*>(&Qw[(long)r32 * QP + d0 * 16 + hi * 8]);
;     float gsc[7];
; #pragma unroll
;     for (int j = 0; j < 7; ++j) {
;         float s = 0.f;
;         if (j < qb) {
;             const float* km = kms + (size_t)(b * NBLK + j) * AW + h * HD + hi * 8;
; #pragma unroll
;             for (int d0 = 0; d0 < 4; ++d0) {
;                 const f32x4 k0 = *(const f32x4*)(km + d0 * 16), k1 = *(const f32x4*)(km + d0 * 16 + 4);
;                 s += (float)qr[d0][0] * k0[0] + (float)qr[d0][1] * k0[1] + (float)qr[d0][2] * k0[2] + (float)qr[d0][3] * k0[3];
;                 s += (float)qr[d0][4] * k1[0] + (float)qr[d0][5] * k1[1] + (float)qr[d0][6] * k1[2] + (float)qr[d0][7] * k1[3];
;             }
;             s += __shfl_xor(s, 32);
.LBB0_530:
	v_mov_b32_e32 v150, v0
	s_and_b64 s[0:1], s[2:3], exec
	s_cselect_b32 s70, s7, s78
	v_readfirstlane_b32 s24, v150
	v_and_b32_e32 v201, 63, v150
	s_ashr_i32 s29, s24, 6
	v_lshlrev_b32_e32 v190, 10, v201
	s_lshl_b32 s0, s29, 3
	v_lshl_add_u64 v[2:3], s[58:59], 0, v[190:191]
	s_ashr_i32 s1, s0, 31
	v_lshl_add_u64 v[182:183], s[0:1], 1, v[2:3]
	s_lshl_b32 s0, s29, 4
	v_bfe_u32 v2, v150, 2, 4
	v_and_or_b32 v2, s0, 48, v2
	s_ashr_i32 s0, s24, 3
	s_lshl_b32 s71, s70, 8
	s_andn2_b32 s0, s0, 31
	s_or_b32 s8, s56, s71
	v_lshlrev_b32_e32 v190, 10, v2
	s_ashr_i32 s1, s0, 31
	s_lshl_b32 s11, s29, 10
	v_lshl_add_u64 v[2:3], s[60:61], 0, v[190:191]
	v_lshlrev_b32_e32 v202, 3, v150
	s_cmp_lg_u32 0, -1
	v_lshl_add_u64 v[2:3], s[0:1], 1, v[2:3]
	v_and_b32_e32 v203, 24, v202
	s_cselect_b32 s0, 0, 0
	v_lshlrev_b32_e32 v190, 1, v203
	s_add_i32 s76, s11, s0
	s_mov_b32 s0, m0
	s_mov_b32 m0, s76
	s_nop 0
	global_load_lds_dwordx4 v[182:183], off
	s_mov_b32 m0, s0
	v_lshl_add_u64 v[104:105], v[2:3], 0, v[190:191]
	s_add_i32 s77, s76, 0x6000
	s_mov_b32 s0, m0
	s_mov_b32 m0, s77
	s_nop 0
	global_load_lds_dwordx4 v[104:105], off
	s_mov_b32 m0, s0
	v_lshl_add_u64 v[2:3], v[182:183], 0, s[42:43]
	s_add_i32 s0, s76, 0x2000
	s_mov_b32 s1, m0
	s_mov_b32 m0, s0
	s_nop 0
	global_load_lds_dwordx4 v[2:3], off
	s_mov_b32 m0, s1
	s_cmp_gt_u32 s70, 3
	s_cselect_b64 s[4:5], -1, 0
	s_cmp_lt_u32 s70, 4
	v_mov_b32_e32 v210, -1
	s_cbranch_scc1 .LBB0_538
	s_lshl_b32 s9, s29, 11
	s_add_u32 s36, s62, s64
	s_addc_u32 s37, s63, s65
	s_add_u32 s36, s36, s9
	s_addc_u32 s37, s37, 0
	v_lshlrev_b32_e32 v19, 2, v201
	global_load_dword v18, v19, s[36:37]
	s_lshl_b32 s0, s29, 5
	s_add_u32 s0, s8, s0
	s_addc_u32 s1, s57, 0
	s_lshl_b64 s[0:1], s[0:1], 11
	s_add_u32 s0, s79, s0
	s_addc_u32 s1, s14, s1
	v_and_b32_e32 v21, 31, v201
	v_lshrrev_b32_e32 v20, 5, v201
	v_lshlrev_b32_e32 v21, 11, v21
	v_lshl_or_b32 v21, v20, 4, v21
	global_load_dwordx4 v[2:5], v21, s[0:1]
	global_load_dwordx4 v[6:9], v21, s[0:1] offset:32
	global_load_dwordx4 v[10:13], v21, s[0:1] offset:64
	global_load_dwordx4 v[14:17], v21, s[0:1] offset:96
	s_mov_b32 s9, 0x15000
	s_lshl_b32 s30, s29, 8
	s_add_i32 s30, s30, s9
	v_add_u32_e32 v101, s30, v19
	v_lshl_add_u32 v100, v20, 5, s9
	s_waitcnt vmcnt(4)
	ds_write_b32 v101, v18
	s_waitcnt lgkmcnt(0)
	s_barrier
	ds_read_b128 v[54:57], v100 offset:0
	ds_read_b128 v[58:61], v100 offset:16
	ds_read_b128 v[62:65], v100 offset:64
	ds_read_b128 v[66:69], v100 offset:80
	ds_read_b128 v[70:73], v100 offset:128
	ds_read_b128 v[74:77], v100 offset:144
	ds_read_b128 v[78:81], v100 offset:192
	ds_read_b128 v[82:85], v100 offset:208
	ds_read_b128 v[106:109], v100 offset:256
	ds_read_b128 v[110:113], v100 offset:272
	ds_read_b128 v[114:117], v100 offset:320
	ds_read_b128 v[118:121], v100 offset:336
	ds_read_b128 v[122:125], v100 offset:384
	ds_read_b128 v[126:129], v100 offset:400
	ds_read_b128 v[130:133], v100 offset:448
	ds_read_b128 v[134:137], v100 offset:464
	s_waitcnt vmcnt(0)
	v_cvt_f32_f16_e32 v22, v2
	v_cvt_f32_f16_sdwa v23, v2 dst_sel:DWORD dst_unused:UNUSED_PAD src0_sel:WORD_1
	v_cvt_f32_f16_e32 v24, v3
	v_cvt_f32_f16_sdwa v25, v3 dst_sel:DWORD dst_unused:UNUSED_PAD src0_sel:WORD_1
	v_cvt_f32_f16_e32 v26, v4
	v_cvt_f32_f16_sdwa v27, v4 dst_sel:DWORD dst_unused:UNUSED_PAD src0_sel:WORD_1
	v_cvt_f32_f16_e32 v28, v5
	v_cvt_f32_f16_sdwa v29, v5 dst_sel:DWORD dst_unused:UNUSED_PAD src0_sel:WORD_1
	v_cvt_f32_f16_e32 v30, v6
	v_cvt_f32_f16_sdwa v31, v6 dst_sel:DWORD dst_unused:UNUSED_PAD src0_sel:WORD_1
	v_cvt_f32_f16_e32 v32, v7
	v_cvt_f32_f16_sdwa v33, v7 dst_sel:DWORD dst_unused:UNUSED_PAD src0_sel:WORD_1
	v_cvt_f32_f16_e32 v34, v8
	v_cvt_f32_f16_sdwa v35, v8 dst_sel:DWORD dst_unused:UNUSED_PAD src0_sel:WORD_1
	v_cvt_f32_f16_e32 v36, v9
	v_cvt_f32_f16_sdwa v37, v9 dst_sel:DWORD dst_unused:UNUSED_PAD src0_sel:WORD_1
	v_cvt_f32_f16_e32 v38, v10
	v_cvt_f32_f16_sdwa v39, v10 dst_sel:DWORD dst_unused:UNUSED_PAD src0_sel:WORD_1
	v_cvt_f32_f16_e32 v40, v11
	v_cvt_f32_f16_sdwa v41, v11 dst_sel:DWORD dst_unused:UNUSED_PAD src0_sel:WORD_1
	v_cvt_f32_f16_e32 v42, v12
	v_cvt_f32_f16_sdwa v43, v12 dst_sel:DWORD dst_unused:UNUSED_PAD src0_sel:WORD_1
	v_cvt_f32_f16_e32 v44, v13
	v_cvt_f32_f16_sdwa v45, v13 dst_sel:DWORD dst_unused:UNUSED_PAD src0_sel:WORD_1
	v_cvt_f32_f16_e32 v46, v14
	v_cvt_f32_f16_sdwa v47, v14 dst_sel:DWORD dst_unused:UNUSED_PAD src0_sel:WORD_1
	v_cvt_f32_f16_e32 v48, v15
	v_cvt_f32_f16_sdwa v49, v15 dst_sel:DWORD dst_unused:UNUSED_PAD src0_sel:WORD_1
	v_cvt_f32_f16_e32 v50, v16
	v_cvt_f32_f16_sdwa v51, v16 dst_sel:DWORD dst_unused:UNUSED_PAD src0_sel:WORD_1
	v_cvt_f32_f16_e32 v52, v17
	v_cvt_f32_f16_sdwa v53, v17 dst_sel:DWORD dst_unused:UNUSED_PAD src0_sel:WORD_1
	s_waitcnt lgkmcnt(8)
	v_pk_mul_f32 v[86:87], v[22:23], v[54:55]
	v_pk_mul_f32 v[88:89], v[24:25], v[56:57]
	v_pk_fma_f32 v[86:87], v[26:27], v[58:59], v[86:87]
	v_pk_fma_f32 v[88:89], v[28:29], v[60:61], v[88:89]
	v_pk_fma_f32 v[86:87], v[30:31], v[62:63], v[86:87]
	v_pk_fma_f32 v[88:89], v[32:33], v[64:65], v[88:89]
	v_pk_fma_f32 v[86:87], v[34:35], v[66:67], v[86:87]
	v_pk_fma_f32 v[88:89], v[36:37], v[68:69], v[88:89]
	v_pk_fma_f32 v[86:87], v[38:39], v[70:71], v[86:87]
	v_pk_fma_f32 v[88:89], v[40:41], v[72:73], v[88:89]
	v_pk_fma_f32 v[86:87], v[42:43], v[74:75], v[86:87]
	v_pk_fma_f32 v[88:89], v[44:45], v[76:77], v[88:89]
	v_pk_fma_f32 v[86:87], v[46:47], v[78:79], v[86:87]
	v_pk_fma_f32 v[88:89], v[48:49], v[80:81], v[88:89]
	v_pk_fma_f32 v[86:87], v[50:51], v[82:83], v[86:87]
	v_pk_fma_f32 v[88:89], v[52:53], v[84:85], v[88:89]
	ds_read_b128 v[54:57], v100 offset:512
	ds_read_b128 v[58:61], v100 offset:528
	ds_read_b128 v[62:65], v100 offset:576
	ds_read_b128 v[66:69], v100 offset:592
	ds_read_b128 v[70:73], v100 offset:640
	ds_read_b128 v[74:77], v100 offset:656
	ds_read_b128 v[78:81], v100 offset:704
	ds_read_b128 v[82:85], v100 offset:720
	v_pk_add_f32 v[86:87], v[86:87], v[88:89]
	s_nop 0
	v_add_f32_e32 v138, v86, v87
	s_waitcnt lgkmcnt(8)
; __device__ __forceinline__ unsigned moba_select(int b, int h, int qb, const f16_t* Q, const float* __restrict__ kms) {
;     ...
;     for (int j = 0; j < 7; ++j) {
;         float s = 0.f;
;         if (j < qb) {
;             const float* km = kms + (size_t)(b * NBLK + j) * AW + h * HD + hi * 8;
; #pragma unroll
;             for (int d0 = 0; d0 < 4; ++d0) {
;                 const f32x4 k0 = *(const f32x4*)(km + d0 * 16), k1 = *(const f32x4*)(km + d0 * 16 + 4);
;                 s += (float)qr[d0][0] * k0[0] + (float)qr[d0][1] * k0[1] + (float)qr[d0][2] * k0[2] + (float)qr[d0][3] * k0[3];
;                 s += (float)qr[d0][4] * k1[0] + (float)qr[d0][5] * k1[1] + (float)qr[d0][6] * k1[2] + (float)qr[d0][7] * k1[3];
;             }
;             s += __shfl_xor(s, 32);
	v_pk_mul_f32 v[90:91], v[22:23], v[106:107]
	v_pk_mul_f32 v[92:93], v[24:25], v[108:109]
	v_pk_fma_f32 v[90:91], v[26:27], v[110:111], v[90:91]
	v_pk_fma_f32 v[92:93], v[28:29], v[112:113], v[92:93]
	v_pk_fma_f32 v[90:91], v[30:31], v[114:115], v[90:91]
	v_pk_fma_f32 v[92:93], v[32:33], v[116:117], v[92:93]
	v_pk_fma_f32 v[90:91], v[34:35], v[118:119], v[90:91]
	v_pk_fma_f32 v[92:93], v[36:37], v[120:121], v[92:93]
	v_pk_fma_f32 v[90:91], v[38:39], v[122:123], v[90:91]
	v_pk_fma_f32 v[92:93], v[40:41], v[124:125], v[92:93]
	v_pk_fma_f32 v[90:91], v[42:43], v[126:127], v[90:91]
	v_pk_fma_f32 v[92:93], v[44:45], v[128:129], v[92:93]
	v_pk_fma_f32 v[90:91], v[46:47], v[130:131], v[90:91]
	v_pk_fma_f32 v[92:93], v[48:49], v[132:133], v[92:93]
	v_pk_fma_f32 v[90:91], v[50:51], v[134:135], v[90:91]
	v_pk_fma_f32 v[92:93], v[52:53], v[136:137], v[92:93]
	ds_read_b128 v[106:109], v100 offset:768
	ds_read_b128 v[110:113], v100 offset:784
	ds_read_b128 v[114:117], v100 offset:832
	ds_read_b128 v[118:121], v100 offset:848
	ds_read_b128 v[122:125], v100 offset:896
	ds_read_b128 v[126:129], v100 offset:912
	ds_read_b128 v[130:133], v100 offset:960
	ds_read_b128 v[134:137], v100 offset:976
	v_pk_add_f32 v[90:91], v[90:91], v[92:93]
	s_nop 0
	v_add_f32_e32 v139, v90, v91
	s_waitcnt lgkmcnt(8)
	v_pk_mul_f32 v[86:87], v[22:23], v[54:55]
	v_pk_mul_f32 v[88:89], v[24:25], v[56:57]
	v_pk_fma_f32 v[86:87], v[26:27], v[58:59], v[86:87]
	v_pk_fma_f32 v[88:89], v[28:29], v[60:61], v[88:89]
	v_pk_fma_f32 v[86:87], v[30:31], v[62:63], v[86:87]
	v_pk_fma_f32 v[88:89], v[32:33], v[64:65], v[88:89]
	v_pk_fma_f32 v[86:87], v[34:35], v[66:67], v[86:87]
	v_pk_fma_f32 v[88:89], v[36:37], v[68:69], v[88:89]
	v_pk_fma_f32 v[86:87], v[38:39], v[70:71], v[86:87]
	v_pk_fma_f32 v[88:89], v[40:41], v[72:73], v[88:89]
	v_pk_fma_f32 v[86:87], v[42:43], v[74:75], v[86:87]
	v_pk_fma_f32 v[88:89], v[44:45], v[76:77], v[88:89]
	v_pk_fma_f32 v[86:87], v[46:47], v[78:79], v[86:87]
	v_pk_fma_f32 v[88:89], v[48:49], v[80:81], v[88:89]
	v_pk_fma_f32 v[86:87], v[50:51], v[82:83], v[86:87]
	v_pk_fma_f32 v[88:89], v[52:53], v[84:85], v[88:89]
	ds_read_b128 v[54:57], v100 offset:1024
	ds_read_b128 v[58:61], v100 offset:1040
	ds_read_b128 v[62:65], v100 offset:1088
	ds_read_b128 v[66:69], v100 offset:1104
	ds_read_b128 v[70:73], v100 offset:1152
	ds_read_b128 v[74:77], v100 offset:1168
	ds_read_b128 v[78:81], v100 offset:1216
	ds_read_b128 v[82:85], v100 offset:1232
	v_pk_add_f32 v[86:87], v[86:87], v[88:89]
	s_nop 0
	v_add_f32_e32 v140, v86, v87
	s_waitcnt lgkmcnt(8)
	v_pk_mul_f32 v[90:91], v[22:23], v[106:107]
	v_pk_mul_f32 v[92:93], v[24:25], v[108:109]
	v_pk_fma_f32 v[90:91], v[26:27], v[110:111], v[90:91]
	v_pk_fma_f32 v[92:93], v[28:29], v[112:113], v[92:93]
	v_pk_fma_f32 v[90:91], v[30:31], v[114:115], v[90:91]
	v_pk_fma_f32 v[92:93], v[32:33], v[116:117], v[92:93]
	v_pk_fma_f32 v[90:91], v[34:35], v[118:119], v[90:91]
	v_pk_fma_f32 v[92:93], v[36:37], v[120:121], v[92:93]
	v_pk_fma_f32 v[90:91], v[38:39], v[122:123], v[90:91]
	v_pk_fma_f32 v[92:93], v[40:41], v[124:125], v[92:93]
	v_pk_fma_f32 v[90:91], v[42:43], v[126:127], v[90:91]
	v_pk_fma_f32 v[92:93], v[44:45], v[128:129], v[92:93]
	v_pk_fma_f32 v[90:91], v[46:47], v[130:131], v[90:91]
	v_pk_fma_f32 v[92:93], v[48:49], v[132:133], v[92:93]
	v_pk_fma_f32 v[90:91], v[50:51], v[134:135], v[90:91]
	v_pk_fma_f32 v[92:93], v[52:53], v[136:137], v[92:93]
	ds_read_b128 v[106:109], v100 offset:1280
	ds_read_b128 v[110:113], v100 offset:1296
	ds_read_b128 v[114:117], v100 offset:1344
	ds_read_b128 v[118:121], v100 offset:1360
	ds_read_b128 v[122:125], v100 offset:1408
	ds_read_b128 v[126:129], v100 offset:1424
	ds_read_b128 v[130:133], v100 offset:1472
	ds_read_b128 v[134:137], v100 offset:1488
	v_pk_add_f32 v[90:91], v[90:91], v[92:93]
	s_nop 0
	v_add_f32_e32 v141, v90, v91
	s_waitcnt lgkmcnt(8)
	v_pk_mul_f32 v[86:87], v[22:23], v[54:55]
	v_pk_mul_f32 v[88:89], v[24:25], v[56:57]
	v_pk_fma_f32 v[86:87], v[26:27], v[58:59], v[86:87]
	v_pk_fma_f32 v[88:89], v[28:29], v[60:61], v[88:89]
	v_pk_fma_f32 v[86:87], v[30:31], v[62:63], v[86:87]
	v_pk_fma_f32 v[88:89], v[32:33], v[64:65], v[88:89]
	v_pk_fma_f32 v[86:87], v[34:35], v[66:67], v[86:87]
	v_pk_fma_f32 v[88:89], v[36:37], v[68:69], v[88:89]
	v_pk_fma_f32 v[86:87], v[38:39], v[70:71], v[86:87]
	v_pk_fma_f32 v[88:89], v[40:41], v[72:73], v[88:89]
	v_pk_fma_f32 v[86:87], v[42:43], v[74:75], v[86:87]
	v_pk_fma_f32 v[88:89], v[44:45], v[76:77], v[88:89]
	v_pk_fma_f32 v[86:87], v[46:47], v[78:79], v[86:87]
	v_pk_fma_f32 v[88:89], v[48:49], v[80:81], v[88:89]
	v_pk_fma_f32 v[86:87], v[50:51], v[82:83], v[86:87]
	v_pk_fma_f32 v[88:89], v[52:53], v[84:85], v[88:89]
	ds_read_b128 v[54:57], v100 offset:1536
	ds_read_b128 v[58:61], v100 offset:1552
	ds_read_b128 v[62:65], v100 offset:1600
	ds_read_b128 v[66:69], v100 offset:1616
	ds_read_b128 v[70:73], v100 offset:1664
	ds_read_b128 v[74:77], v100 offset:1680
	ds_read_b128 v[78:81], v100 offset:1728
	ds_read_b128 v[82:85], v100 offset:1744
	v_pk_add_f32 v[86:87], v[86:87], v[88:89]
	s_nop 0
	v_add_f32_e32 v142, v86, v87
	s_waitcnt lgkmcnt(8)
	v_pk_mul_f32 v[90:91], v[22:23], v[106:107]
	v_pk_mul_f32 v[92:93], v[24:25], v[108:109]
	v_pk_fma_f32 v[90:91], v[26:27], v[110:111], v[90:91]
	v_pk_fma_f32 v[92:93], v[28:29], v[112:113], v[92:93]
	v_pk_fma_f32 v[90:91], v[30:31], v[114:115], v[90:91]
	v_pk_fma_f32 v[92:93], v[32:33], v[116:117], v[92:93]
	v_pk_fma_f32 v[90:91], v[34:35], v[118:119], v[90:91]
	v_pk_fma_f32 v[92:93], v[36:37], v[120:121], v[92:93]
	v_pk_fma_f32 v[90:91], v[38:39], v[122:123], v[90:91]
	v_pk_fma_f32 v[92:93], v[40:41], v[124:125], v[92:93]
	v_pk_fma_f32 v[90:91], v[42:43], v[126:127], v[90:91]
	v_pk_fma_f32 v[92:93], v[44:45], v[128:129], v[92:93]
	v_pk_fma_f32 v[90:91], v[46:47], v[130:131], v[90:91]
	v_pk_fma_f32 v[92:93], v[48:49], v[132:133], v[92:93]
	v_pk_fma_f32 v[90:91], v[50:51], v[134:135], v[90:91]
	v_pk_fma_f32 v[92:93], v[52:53], v[136:137], v[92:93]
	s_nop 0
	v_pk_add_f32 v[90:91], v[90:91], v[92:93]
	s_nop 0
	v_add_f32_e32 v143, v90, v91
	s_waitcnt lgkmcnt(0)
; __device__ __forceinline__ unsigned moba_select(int b, int h, int qb, const f16_t* Q, const float* __restrict__ kms) {
;     ...
;     for (int j = 0; j < 7; ++j) {
;         float s = 0.f;
;         if (j < qb) {
;             const float* km = kms + (size_t)(b * NBLK + j) * AW + h * HD + hi * 8;
; #pragma unroll
;             for (int d0 = 0; d0 < 4; ++d0) {
;                 const f32x4 k0 = *(const f32x4*)(km + d0 * 16), k1 = *(const f32x4*)(km + d0 * 16 + 4);
;                 s += (float)qr[d0][0] * k0[0] + (float)qr[d0][1] * k0[1] + (float)qr[d0][2] * k0[2] + (float)qr[d0][3] * k0[3];
;                 s += (float)qr[d0][4] * k1[0] + (float)qr[d0][5] * k1[1] + (float)qr[d0][6] * k1[2] + (float)qr[d0][7] * k1[3];
;             }
;             s += __shfl_xor(s, 32);
;         } else s = -INFINITY;
;         gsc[j] = s;
;     }
;     unsigned sm = 0u;
; #pragma unroll
;     for (int j = 0; j < 7; ++j) {
;         int cnt = 0;
; #pragma unroll
;         for (int i = 0; i < 7; ++i) { if (i == j) continue; const bool ahead = (gsc[i] > gsc[j]) || (gsc[i] == gsc[j] && i < j); cnt += ahead ? 1 : 0; }
;         if (j < qb && cnt < 3) sm |= (1u << j);
;     }
;     return sm;
	v_pk_mul_f32 v[86:87], v[22:23], v[54:55]
	v_pk_mul_f32 v[88:89], v[24:25], v[56:57]
	v_pk_fma_f32 v[86:87], v[26:27], v[58:59], v[86:87]
	v_pk_fma_f32 v[88:89], v[28:29], v[60:61], v[88:89]
	v_pk_fma_f32 v[86:87], v[30:31], v[62:63], v[86:87]
	v_pk_fma_f32 v[88:89], v[32:33], v[64:65], v[88:89]
	v_pk_fma_f32 v[86:87], v[34:35], v[66:67], v[86:87]
	v_pk_fma_f32 v[88:89], v[36:37], v[68:69], v[88:89]
	v_pk_fma_f32 v[86:87], v[38:39], v[70:71], v[86:87]
	v_pk_fma_f32 v[88:89], v[40:41], v[72:73], v[88:89]
	v_pk_fma_f32 v[86:87], v[42:43], v[74:75], v[86:87]
	v_pk_fma_f32 v[88:89], v[44:45], v[76:77], v[88:89]
	v_pk_fma_f32 v[86:87], v[46:47], v[78:79], v[86:87]
	v_pk_fma_f32 v[88:89], v[48:49], v[80:81], v[88:89]
	v_pk_fma_f32 v[86:87], v[50:51], v[82:83], v[86:87]
	v_pk_fma_f32 v[88:89], v[52:53], v[84:85], v[88:89]
	s_nop 0
	v_pk_add_f32 v[86:87], v[86:87], v[88:89]
	s_nop 0
	v_add_f32_e32 v144, v86, v87
	v_mov_b32_e32 v54, v138
	v_mov_b32_e32 v55, v139
	v_mov_b32_e32 v56, v140
	v_mov_b32_e32 v57, v141
	v_mov_b32_e32 v58, v142
	v_mov_b32_e32 v59, v143
	v_mov_b32_e32 v60, v144
	s_nop 1
	v_permlane32_swap_b32_e32 v138, v54
	v_permlane32_swap_b32_e32 v139, v55
	v_permlane32_swap_b32_e32 v140, v56
	v_permlane32_swap_b32_e32 v141, v57
	v_permlane32_swap_b32_e32 v142, v58
	v_permlane32_swap_b32_e32 v143, v59
	v_permlane32_swap_b32_e32 v144, v60
	v_add_f32_e32 v138, v138, v54
	v_add_f32_e32 v139, v139, v55
	v_add_f32_e32 v140, v140, v56
	v_add_f32_e32 v141, v141, v57
	v_add_f32_e32 v142, v142, v58
	v_add_f32_e32 v143, v143, v59
	v_add_f32_e32 v144, v144, v60
	v_mov_b32_e32 v146, 0xff800000
	s_cmp_gt_u32 s70, 4
	s_cselect_b64 s[30:31], -1, 0
	v_cndmask_b32_e64 v142, v146, v142, s[30:31]
	s_cmp_gt_u32 s70, 5
	s_cselect_b64 s[30:31], -1, 0
	v_cndmask_b32_e64 v143, v146, v143, s[30:31]
	s_cmp_gt_u32 s70, 6
	s_cselect_b64 s[30:31], -1, 0
	v_cndmask_b32_e64 v144, v146, v144, s[30:31]
	v_mov_b32_e32 v151, 6
	v_mov_b32_e32 v152, 5
	v_mov_b32_e32 v153, 4
	v_mov_b32_e32 v154, 3
	v_mov_b32_e32 v155, 2
	v_mov_b32_e32 v156, 1
	v_mov_b32_e32 v157, 0
	v_cmp_ge_f32_e64 s[0:1], v138, v139
	v_cmp_ge_f32_e64 s[30:31], v138, v140
	v_cmp_ge_f32_e64 s[36:37], v138, v141
	v_addc_co_u32_e64 v152, vcc, 0, v152, s[0:1]
	v_subb_co_u32_e64 v151, vcc, v151, 0, s[0:1]
	v_cmp_ge_f32_e64 s[98:99], v138, v142
	v_addc_co_u32_e64 v153, vcc, 0, v153, s[30:31]
	v_subb_co_u32_e64 v151, vcc, v151, 0, s[30:31]
	v_cmp_ge_f32_e64 s[0:1], v138, v143
	v_addc_co_u32_e64 v154, vcc, 0, v154, s[36:37]
	v_subb_co_u32_e64 v151, vcc, v151, 0, s[36:37]
	v_cmp_ge_f32_e64 s[30:31], v138, v144
	v_addc_co_u32_e64 v155, vcc, 0, v155, s[98:99]
	v_subb_co_u32_e64 v151, vcc, v151, 0, s[98:99]
	v_cmp_ge_f32_e64 s[36:37], v139, v140
	v_addc_co_u32_e64 v156, vcc, 0, v156, s[0:1]
	v_subb_co_u32_e64 v151, vcc, v151, 0, s[0:1]
	v_cmp_ge_f32_e64 s[98:99], v139, v141
	v_addc_co_u32_e64 v157, vcc, 0, v157, s[30:31]
	v_subb_co_u32_e64 v151, vcc, v151, 0, s[30:31]
	v_cmp_ge_f32_e64 s[0:1], v139, v142
	v_addc_co_u32_e64 v153, vcc, 0, v153, s[36:37]
	v_subb_co_u32_e64 v152, vcc, v152, 0, s[36:37]
	v_cmp_ge_f32_e64 s[30:31], v139, v143
	v_addc_co_u32_e64 v154, vcc, 0, v154, s[98:99]
	v_subb_co_u32_e64 v152, vcc, v152, 0, s[98:99]
	v_cmp_ge_f32_e64 s[36:37], v139, v144
	v_addc_co_u32_e64 v155, vcc, 0, v155, s[0:1]
	v_subb_co_u32_e64 v152, vcc, v152, 0, s[0:1]
	v_cmp_ge_f32_e64 s[98:99], v140, v141
	v_addc_co_u32_e64 v156, vcc, 0, v156, s[30:31]
	v_subb_co_u32_e64 v152, vcc, v152, 0, s[30:31]
	v_cmp_ge_f32_e64 s[0:1], v140, v142
	v_addc_co_u32_e64 v157, vcc, 0, v157, s[36:37]
	v_subb_co_u32_e64 v152, vcc, v152, 0, s[36:37]
	v_cmp_ge_f32_e64 s[30:31], v140, v143
	v_addc_co_u32_e64 v154, vcc, 0, v154, s[98:99]
	v_subb_co_u32_e64 v153, vcc, v153, 0, s[98:99]
	v_cmp_ge_f32_e64 s[36:37], v140, v144
	v_addc_co_u32_e64 v155, vcc, 0, v155, s[0:1]
	v_subb_co_u32_e64 v153, vcc, v153, 0, s[0:1]
	v_cmp_ge_f32_e64 s[98:99], v141, v142
	v_addc_co_u32_e64 v156, vcc, 0, v156, s[30:31]
	v_subb_co_u32_e64 v153, vcc, v153, 0, s[30:31]
	v_cmp_ge_f32_e64 s[0:1], v141, v143
	v_addc_co_u32_e64 v157, vcc, 0, v157, s[36:37]
	v_subb_co_u32_e64 v153, vcc, v153, 0, s[36:37]
	v_cmp_ge_f32_e64 s[30:31], v141, v144
	v_addc_co_u32_e64 v155, vcc, 0, v155, s[98:99]
	v_subb_co_u32_e64 v154, vcc, v154, 0, s[98:99]
	v_cmp_ge_f32_e64 s[36:37], v142, v143
	v_addc_co_u32_e64 v156, vcc, 0, v156, s[0:1]
	v_subb_co_u32_e64 v154, vcc, v154, 0, s[0:1]
	v_cmp_ge_f32_e64 s[98:99], v142, v144
	v_addc_co_u32_e64 v157, vcc, 0, v157, s[30:31]
	v_subb_co_u32_e64 v154, vcc, v154, 0, s[30:31]
	v_cmp_ge_f32_e64 s[0:1], v143, v144
	v_addc_co_u32_e64 v156, vcc, 0, v156, s[36:37]
	v_subb_co_u32_e64 v155, vcc, v155, 0, s[36:37]
	s_nop 0
	v_addc_co_u32_e64 v157, vcc, 0, v157, s[98:99]
	v_subb_co_u32_e64 v155, vcc, v155, 0, s[98:99]
	s_nop 0
	v_addc_co_u32_e64 v157, vcc, 0, v157, s[0:1]
	v_subb_co_u32_e64 v156, vcc, v156, 0, s[0:1]
	s_nop 1
	v_cmp_gt_u32_e64 s[0:1], 3, v151
	v_cmp_gt_u32_e64 s[30:31], 3, v152
	v_cmp_gt_u32_e64 s[36:37], 3, v153
	v_cndmask_b32_e64 v147, 0, 1, s[0:1]
	v_cmp_gt_u32_e64 s[98:99], 3, v154
	v_cndmask_b32_e64 v148, 0, 2, s[30:31]
	v_cmp_gt_u32_e64 s[0:1], 3, v155
	v_cndmask_b32_e64 v149, 0, 4, s[36:37]
	v_cmp_gt_u32_e64 s[30:31], 3, v156
	v_cndmask_b32_e64 v158, 0, 8, s[98:99]
	v_cmp_gt_u32_e64 s[36:37], 3, v157
	v_cndmask_b32_e64 v159, 0, 16, s[0:1]
	s_nop 0
	v_cndmask_b32_e64 v160, 0, 32, s[30:31]
	v_cndmask_b32_e64 v161, 0, 64, s[36:37]
	s_lshl_b32 s9, 1, s70
	s_add_i32 s9, s9, -1
	v_or3_b32 v210, v147, v148, v149
	v_or3_b32 v210, v210, v158, v159
	v_or3_b32 v210, v210, v160, v161
	v_and_b32_e32 v210, s9, v210
